# P3 tail: hand-written dwordx4 2-stage transposer with counted vmcnt
# baseline (speedup 1.0000x reference)
.LBB0_693:
	s_cmp_lt_u32 s2, 8
	s_barrier
	s_cbranch_scc1 .LBB0_950
	s_mov_b64 exec, -1
	v_readlane_b32 s0, v254, 0
	v_readlane_b32 s1, v254, 1
	s_nop 4
	s_load_dwordx2 s[56:57], s[0:1], 0xa8
	s_load_dwordx2 s[58:59], s[0:1], 0xc0
	s_load_dwordx2 s[60:61], s[0:1], 0x88
	s_load_dwordx2 s[62:63], s[0:1], 0x78
	s_load_dwordx2 s[64:65], s[0:1], 0x80
	s_load_dwordx2 s[66:67], s[0:1], 0x90
	s_load_dwordx2 s[68:69], s[0:1], 0xa0
	s_load_dwordx2 s[70:71], s[0:1], 0x48
	s_load_dwordx2 s[72:73], s[0:1], 0xd8
	s_load_dword s3, s[0:1], 0xe8
	v_readfirstlane_b32 s4, v0
	v_and_b32_e32 v7, 63, v0
	s_lshr_b32 s4, s4, 6
	v_lshrrev_b32_e32 v1, 3, v7
	v_and_b32_e32 v2, 7, v7
	s_lshl_b32 s5, s4, 14
	v_lshlrev_b32_e32 v5, 5, v2
	s_movk_i32 s10, 0x420
	v_mul_u32_u24_e32 v4, s10, v2
	v_lshlrev_b32_e32 v2, 4, v2
	s_movk_i32 s10, 0x84
	v_mad_u32_u24 v3, v1, s10, v2
	v_lshl_add_u32 v4, v1, 2, v4
	v_add_u32_e32 v3, s5, v3
	v_add_u32_e32 v4, s5, v4
	v_mov_b32_e32 v124, v3
	v_add_u32_e32 v125, 1056, v3
	v_add_u32_e32 v126, 2112, v3
	v_add_u32_e32 v127, 3168, v3
	v_add_u32_e32 v128, 4224, v3
	v_add_u32_e32 v129, 5280, v3
	v_add_u32_e32 v130, 6336, v3
	v_add_u32_e32 v131, 7392, v3
	s_waitcnt lgkmcnt(0)
	s_sub_u32 s5, s2, 8
	s_lshl_b32 s5, s5, 3
	s_add_u32 s20, s5, s4
	s_sub_u32 s21, s3, 8
	s_lshl_b32 s21, s21, 3
	s_cmp_ge_u32 s20, 0x5600
	s_cbranch_scc1 .LBB0_949
	s_mov_b32 s26, s20
	s_cmp_lt_u32 s26, 0x2c00
	s_cbranch_scc1 .Ltrp3_i1_s0
	s_sub_u32 s26, s26, 0x2c00
	s_cmp_lt_u32 s26, 0x1600
	s_cbranch_scc1 .Ltrp3_i1_s1
	s_sub_u32 s26, s26, 0x1600
	s_cmp_lt_u32 s26, 0x800
	s_cbranch_scc1 .Ltrp3_i1_s2
	s_sub_u32 s26, s26, 0x800
	s_cmp_lt_u32 s26, 0x400
	s_cbranch_scc1 .Ltrp3_i1_s3
	s_sub_u32 s26, s26, 0x400
	s_cmp_lt_u32 s26, 0x400
	s_cbranch_scc1 .Ltrp3_i1_s4
	s_sub_u32 s26, s26, 0x400
	s_cmp_lt_u32 s26, 0x200
	s_cbranch_scc1 .Ltrp3_i1_s5
	s_sub_u32 s26, s26, 0x200
	s_branch .Ltrp3_i1_s6
.Ltrp3_i1_s0:
	s_mov_b64 s[22:23], s[56:57]
	s_mov_b32 s24, 0xb000
	s_mul_hi_u32 s25, s26, 0xba2e8c
	s_mul_i32 s27, s25, 0x160
	s_sub_u32 s27, s26, s27
	s_mov_b32 s28, 0x3a00000
	s_mov_b32 s29, 0x1000
	s_mov_b32 s30, 0x6000
	s_mov_b32 s31, 1
	s_branch .Ltrp3_i1_c
.Ltrp3_i1_s1:
	s_mov_b64 s[22:23], s[58:59]
	s_mov_b32 s24, 0x2000
	s_lshr_b32 s25, s26, 6
	s_and_b32 s27, s26, 63
	s_mov_b32 s28, 0x6600000
	s_mov_b32 s29, 0x2c00
	s_mov_b32 s30, 0
	s_mov_b32 s31, 0
	s_branch .Ltrp3_i1_c
.Ltrp3_i1_s2:
	s_mov_b64 s[22:23], s[60:61]
	s_mov_b32 s24, 0x2000
	s_lshr_b32 s25, s26, 6
	s_and_b32 s27, s26, 63
	s_mov_b32 s28, 0x2a00000
	s_mov_b32 s29, 0x1000
	s_mov_b32 s30, 0
	s_mov_b32 s31, 0
	s_branch .Ltrp3_i1_c
.Ltrp3_i1_s3:
	s_mov_b64 s[22:23], s[62:63]
	s_mov_b32 s24, 0x2000
	s_lshr_b32 s25, s26, 6
	s_and_b32 s27, s26, 63
	s_mov_b32 s28, 0x2200000
	s_mov_b32 s29, 0x1000
	s_mov_b32 s30, 0
	s_mov_b32 s31, 0
	s_branch .Ltrp3_i1_c
.Ltrp3_i1_s4:
	s_mov_b64 s[22:23], s[64:65]
	s_mov_b32 s24, 0x2000
	s_lshr_b32 s25, s26, 6
	s_and_b32 s27, s26, 63
	s_mov_b32 s28, 0x2200800
	s_mov_b32 s29, 0x1000
	s_mov_b32 s30, 0
	s_mov_b32 s31, 0
	s_branch .Ltrp3_i1_c
.Ltrp3_i1_s5:
	s_mov_b64 s[22:23], s[66:67]
	s_mov_b32 s24, 0x800
	s_lshr_b32 s25, s26, 4
	s_and_b32 s27, s26, 15
	s_mov_b32 s28, 0x3200000
	s_mov_b32 s29, 0x1000
	s_mov_b32 s30, 0x2000
	s_mov_b32 s31, 1
	s_branch .Ltrp3_i1_c
.Ltrp3_i1_s6:
	s_mov_b64 s[22:23], s[68:69]
	s_mov_b32 s24, 0x2000
	s_lshr_b32 s25, s26, 6
	s_and_b32 s27, s26, 63
	s_mov_b32 s28, 0x3800000
	s_mov_b32 s29, 0x400
	s_mov_b32 s30, 0
	s_mov_b32 s31, 0
.Ltrp3_i1_c:
	s_lshl_b32 s4, s24, 6
	s_mul_i32 s4, s25, s4
	s_lshl_b32 s5, s27, 7
	s_add_u32 s4, s4, s5
	s_add_u32 s10, s22, s4
	s_addc_u32 s11, s23, 0
	v_mad_u32_u24 v6, v1, s24, v2
	s_lshl_b32 s4, s29, 5
	s_mul_i32 s4, s27, s4
	s_lshl_b32 s5, s25, 7
	s_add_u32 s4, s4, s5
	s_add_u32 s4, s4, s28
	s_add_u32 s34, s72, s4
	s_addc_u32 s35, s73, 0
	s_mov_b32 s36, s29
	s_mov_b32 s37, s31
	s_lshl_b32 s4, s25, 8
	s_add_u32 s4, s4, s30
	s_add_u32 s12, s70, s4
	s_addc_u32 s13, s71, 0
	s_lshl_b32 s14, s24, 3
	global_load_dwordx4 v[44:47], v6, s[10:11]
	s_add_u32 s10, s10, s14
	s_addc_u32 s11, s11, 0
	global_load_dwordx4 v[48:51], v6, s[10:11]
	s_add_u32 s10, s10, s14
	s_addc_u32 s11, s11, 0
	global_load_dwordx4 v[52:55], v6, s[10:11]
	s_add_u32 s10, s10, s14
	s_addc_u32 s11, s11, 0
	global_load_dwordx4 v[56:59], v6, s[10:11]
	s_add_u32 s10, s10, s14
	s_addc_u32 s11, s11, 0
	global_load_dwordx4 v[60:63], v6, s[10:11]
	s_add_u32 s10, s10, s14
	s_addc_u32 s11, s11, 0
	global_load_dwordx4 v[64:67], v6, s[10:11]
	s_add_u32 s10, s10, s14
	s_addc_u32 s11, s11, 0
	global_load_dwordx4 v[68:71], v6, s[10:11]
	s_add_u32 s10, s10, s14
	s_addc_u32 s11, s11, 0
	global_load_dwordx4 v[72:75], v6, s[10:11]
	global_load_dwordx4 v[76:79], v5, s[12:13]
	global_load_dwordx4 v[80:83], v5, s[12:13] offset:16
	s_add_u32 s20, s20, s21
	s_cmp_ge_u32 s20, 0x5600
	s_mov_b32 s43, 0
	s_cbranch_scc1 .Ltrp3_pro_nob
	s_mov_b32 s26, s20
	s_cmp_lt_u32 s26, 0x2c00
	s_cbranch_scc1 .Ltrp3_i2_s0
	s_sub_u32 s26, s26, 0x2c00
	s_cmp_lt_u32 s26, 0x1600
	s_cbranch_scc1 .Ltrp3_i2_s1
	s_sub_u32 s26, s26, 0x1600
	s_cmp_lt_u32 s26, 0x800
	s_cbranch_scc1 .Ltrp3_i2_s2
	s_sub_u32 s26, s26, 0x800
	s_cmp_lt_u32 s26, 0x400
	s_cbranch_scc1 .Ltrp3_i2_s3
	s_sub_u32 s26, s26, 0x400
	s_cmp_lt_u32 s26, 0x400
	s_cbranch_scc1 .Ltrp3_i2_s4
	s_sub_u32 s26, s26, 0x400
	s_cmp_lt_u32 s26, 0x200
	s_cbranch_scc1 .Ltrp3_i2_s5
	s_sub_u32 s26, s26, 0x200
	s_branch .Ltrp3_i2_s6

.Ltrp3_i2_c:
	s_lshl_b32 s4, s24, 6
	s_mul_i32 s4, s25, s4
	s_lshl_b32 s5, s27, 7
	s_add_u32 s4, s4, s5
	s_add_u32 s10, s22, s4
	s_addc_u32 s11, s23, 0
	v_mad_u32_u24 v6, v1, s24, v2
	s_lshl_b32 s4, s29, 5
	s_mul_i32 s4, s27, s4
	s_lshl_b32 s5, s25, 7
	s_add_u32 s4, s4, s5
	s_add_u32 s4, s4, s28
	s_add_u32 s38, s72, s4
	s_addc_u32 s39, s73, 0
	s_mov_b32 s40, s29
	s_mov_b32 s41, s31
	s_lshl_b32 s4, s25, 8
	s_add_u32 s4, s4, s30
	s_add_u32 s12, s70, s4
	s_addc_u32 s13, s71, 0
	s_lshl_b32 s14, s24, 3
	global_load_dwordx4 v[84:87], v6, s[10:11]
	s_add_u32 s10, s10, s14
	s_addc_u32 s11, s11, 0
	global_load_dwordx4 v[88:91], v6, s[10:11]
	s_add_u32 s10, s10, s14
	s_addc_u32 s11, s11, 0
	global_load_dwordx4 v[92:95], v6, s[10:11]
	s_add_u32 s10, s10, s14
	s_addc_u32 s11, s11, 0
	global_load_dwordx4 v[96:99], v6, s[10:11]
	s_add_u32 s10, s10, s14
	s_addc_u32 s11, s11, 0
	global_load_dwordx4 v[100:103], v6, s[10:11]
	s_add_u32 s10, s10, s14
	s_addc_u32 s11, s11, 0
	global_load_dwordx4 v[104:107], v6, s[10:11]
	s_add_u32 s10, s10, s14
	s_addc_u32 s11, s11, 0
	global_load_dwordx4 v[108:111], v6, s[10:11]
	s_add_u32 s10, s10, s14
	s_addc_u32 s11, s11, 0
	global_load_dwordx4 v[112:115], v6, s[10:11]
	global_load_dwordx4 v[116:119], v5, s[12:13]
	global_load_dwordx4 v[120:123], v5, s[12:13] offset:16
	s_add_u32 s20, s20, s21
	s_mov_b32 s43, 1
	s_waitcnt vmcnt(10)
	s_branch .Ltrp3_loopA

.Ltrp3_loopA:
	ds_write2_b32 v124, v44, v45 offset1:1
	ds_write2_b32 v124, v46, v47 offset0:2 offset1:3
	ds_write2_b32 v125, v48, v49 offset1:1
	ds_write2_b32 v125, v50, v51 offset0:2 offset1:3
	ds_write2_b32 v126, v52, v53 offset1:1
	ds_write2_b32 v126, v54, v55 offset0:2 offset1:3
	ds_write2_b32 v127, v56, v57 offset1:1
	ds_write2_b32 v127, v58, v59 offset0:2 offset1:3
	ds_write2_b32 v128, v60, v61 offset1:1
	ds_write2_b32 v128, v62, v63 offset0:2 offset1:3
	ds_write2_b32 v129, v64, v65 offset1:1
	ds_write2_b32 v129, v66, v67 offset0:2 offset1:3
	ds_write2_b32 v130, v68, v69 offset1:1
	ds_write2_b32 v130, v70, v71 offset0:2 offset1:3
	ds_write2_b32 v131, v72, v73 offset1:1
	ds_write2_b32 v131, v74, v75 offset0:2 offset1:3
	v_mad_u32_u24 v8, v1, s36, v2
	s_lshl_b32 s4, s36, 3
	s_nop 0
	v_add_u32_e32 v9, s4, v8
	v_add_u32_e32 v10, s4, v9
	v_add_u32_e32 v11, s4, v10
	s_waitcnt lgkmcnt(0)
	ds_read2_b32 v[12:13], v4 offset1:33
	ds_read2_b32 v[14:15], v4 offset0:66 offset1:99
	ds_read2_b32 v[16:17], v4 offset0:132 offset1:165
	ds_read2_b32 v[18:19], v4 offset0:198 offset1:231
	ds_read2_b32 v[20:21], v4 offset0:8 offset1:41
	ds_read2_b32 v[22:23], v4 offset0:74 offset1:107
	ds_read2_b32 v[24:25], v4 offset0:140 offset1:173
	ds_read2_b32 v[26:27], v4 offset0:206 offset1:239
	ds_read2_b32 v[28:29], v4 offset0:16 offset1:49
	ds_read2_b32 v[30:31], v4 offset0:82 offset1:115
	ds_read2_b32 v[32:33], v4 offset0:148 offset1:181
	ds_read2_b32 v[34:35], v4 offset0:214 offset1:247
	ds_read2_b32 v[36:37], v4 offset0:24 offset1:57
	ds_read2_b32 v[38:39], v4 offset0:90 offset1:123
	ds_read2_b32 v[40:41], v4 offset0:156 offset1:189
	ds_read2_b32 v[42:43], v4 offset0:222 offset1:255
	s_cmp_eq_u32 s37, 0
	s_waitcnt lgkmcnt(0)
	s_cbranch_scc1 .Ltrp3_p3_ng
	v_mul_f32_e32 v12, v76, v12
	v_mul_f32_e32 v13, v77, v13
	v_mul_f32_e32 v14, v78, v14
	v_mul_f32_e32 v15, v79, v15
	v_mul_f32_e32 v16, v80, v16
	v_mul_f32_e32 v17, v81, v17
	v_mul_f32_e32 v18, v82, v18
	v_mul_f32_e32 v19, v83, v19
	v_mul_f32_e32 v20, v76, v20
	v_mul_f32_e32 v21, v77, v21
	v_mul_f32_e32 v22, v78, v22
	v_mul_f32_e32 v23, v79, v23
	v_mul_f32_e32 v24, v80, v24
	v_mul_f32_e32 v25, v81, v25
	v_mul_f32_e32 v26, v82, v26
	v_mul_f32_e32 v27, v83, v27
	v_mul_f32_e32 v28, v76, v28
	v_mul_f32_e32 v29, v77, v29
	v_mul_f32_e32 v30, v78, v30
	v_mul_f32_e32 v31, v79, v31
	v_mul_f32_e32 v32, v80, v32
	v_mul_f32_e32 v33, v81, v33
	v_mul_f32_e32 v34, v82, v34
	v_mul_f32_e32 v35, v83, v35
	v_mul_f32_e32 v36, v76, v36
	v_mul_f32_e32 v37, v77, v37
	v_mul_f32_e32 v38, v78, v38
	v_mul_f32_e32 v39, v79, v39
	v_mul_f32_e32 v40, v80, v40
	v_mul_f32_e32 v41, v81, v41
	v_mul_f32_e32 v42, v82, v42
	v_mul_f32_e32 v43, v83, v43
.Ltrp3_p3_ng:
	v_cvt_pk_bf16_f32 v12, v12, v13
	v_cvt_pk_bf16_f32 v13, v14, v15
	v_cvt_pk_bf16_f32 v14, v16, v17
	v_cvt_pk_bf16_f32 v15, v18, v19
	v_cvt_pk_bf16_f32 v20, v20, v21
	v_cvt_pk_bf16_f32 v21, v22, v23
	v_cvt_pk_bf16_f32 v22, v24, v25
	v_cvt_pk_bf16_f32 v23, v26, v27
	v_cvt_pk_bf16_f32 v28, v28, v29
	v_cvt_pk_bf16_f32 v29, v30, v31
	v_cvt_pk_bf16_f32 v30, v32, v33
	v_cvt_pk_bf16_f32 v31, v34, v35
	v_cvt_pk_bf16_f32 v36, v36, v37
	v_cvt_pk_bf16_f32 v37, v38, v39
	v_cvt_pk_bf16_f32 v38, v40, v41
	v_cvt_pk_bf16_f32 v39, v42, v43
	global_store_dwordx4 v8, v[12:15], s[34:35]
	global_store_dwordx4 v9, v[20:23], s[34:35]
	global_store_dwordx4 v10, v[28:31], s[34:35]
	global_store_dwordx4 v11, v[36:39], s[34:35]
	s_cmp_ge_u32 s20, 0x5600
	s_mov_b32 s42, 0
	s_cbranch_scc1 .Ltrp3_skipA
	s_mov_b32 s26, s20
	s_cmp_lt_u32 s26, 0x2c00
	s_cbranch_scc1 .Ltrp3_i4_s0
	s_sub_u32 s26, s26, 0x2c00
	s_cmp_lt_u32 s26, 0x1600
	s_cbranch_scc1 .Ltrp3_i4_s1
	s_sub_u32 s26, s26, 0x1600
	s_cmp_lt_u32 s26, 0x800
	s_cbranch_scc1 .Ltrp3_i4_s2
	s_sub_u32 s26, s26, 0x800
	s_cmp_lt_u32 s26, 0x400
	s_cbranch_scc1 .Ltrp3_i4_s3
	s_sub_u32 s26, s26, 0x400
	s_cmp_lt_u32 s26, 0x400
	s_cbranch_scc1 .Ltrp3_i4_s4
	s_sub_u32 s26, s26, 0x400
	s_cmp_lt_u32 s26, 0x200
	s_cbranch_scc1 .Ltrp3_i4_s5
	s_sub_u32 s26, s26, 0x200
	s_branch .Ltrp3_i4_s6

.Ltrp3_i4_c:
	s_lshl_b32 s4, s24, 6
	s_mul_i32 s4, s25, s4
	s_lshl_b32 s5, s27, 7
	s_add_u32 s4, s4, s5
	s_add_u32 s10, s22, s4
	s_addc_u32 s11, s23, 0
	v_mad_u32_u24 v6, v1, s24, v2
	s_lshl_b32 s4, s29, 5
	s_mul_i32 s4, s27, s4
	s_lshl_b32 s5, s25, 7
	s_add_u32 s4, s4, s5
	s_add_u32 s4, s4, s28
	s_add_u32 s34, s72, s4
	s_addc_u32 s35, s73, 0
	s_mov_b32 s36, s29
	s_mov_b32 s37, s31
	s_lshl_b32 s4, s25, 8
	s_add_u32 s4, s4, s30
	s_add_u32 s12, s70, s4
	s_addc_u32 s13, s71, 0
	s_lshl_b32 s14, s24, 3
	global_load_dwordx4 v[44:47], v6, s[10:11]
	s_add_u32 s10, s10, s14
	s_addc_u32 s11, s11, 0
	global_load_dwordx4 v[48:51], v6, s[10:11]
	s_add_u32 s10, s10, s14
	s_addc_u32 s11, s11, 0
	global_load_dwordx4 v[52:55], v6, s[10:11]
	s_add_u32 s10, s10, s14
	s_addc_u32 s11, s11, 0
	global_load_dwordx4 v[56:59], v6, s[10:11]
	s_add_u32 s10, s10, s14
	s_addc_u32 s11, s11, 0
	global_load_dwordx4 v[60:63], v6, s[10:11]
	s_add_u32 s10, s10, s14
	s_addc_u32 s11, s11, 0
	global_load_dwordx4 v[64:67], v6, s[10:11]
	s_add_u32 s10, s10, s14
	s_addc_u32 s11, s11, 0
	global_load_dwordx4 v[68:71], v6, s[10:11]
	s_add_u32 s10, s10, s14
	s_addc_u32 s11, s11, 0
	global_load_dwordx4 v[72:75], v6, s[10:11]
	global_load_dwordx4 v[76:79], v5, s[12:13]
	global_load_dwordx4 v[80:83], v5, s[12:13] offset:16
	s_add_u32 s20, s20, s21
	s_mov_b32 s42, 1
.Ltrp3_skipA:
	s_cmp_eq_u32 s43, 0
	s_cbranch_scc1 .LBB0_949
	s_cmp_eq_u32 s42, 0
	s_cbranch_scc1 .Ltrp3_wB0
	s_waitcnt vmcnt(14)
	s_branch .Ltrp3_doB

.Ltrp3_doB:
	ds_write2_b32 v124, v84, v85 offset1:1
	ds_write2_b32 v124, v86, v87 offset0:2 offset1:3
	ds_write2_b32 v125, v88, v89 offset1:1
	ds_write2_b32 v125, v90, v91 offset0:2 offset1:3
	ds_write2_b32 v126, v92, v93 offset1:1
	ds_write2_b32 v126, v94, v95 offset0:2 offset1:3
	ds_write2_b32 v127, v96, v97 offset1:1
	ds_write2_b32 v127, v98, v99 offset0:2 offset1:3
	ds_write2_b32 v128, v100, v101 offset1:1
	ds_write2_b32 v128, v102, v103 offset0:2 offset1:3
	ds_write2_b32 v129, v104, v105 offset1:1
	ds_write2_b32 v129, v106, v107 offset0:2 offset1:3
	ds_write2_b32 v130, v108, v109 offset1:1
	ds_write2_b32 v130, v110, v111 offset0:2 offset1:3
	ds_write2_b32 v131, v112, v113 offset1:1
	ds_write2_b32 v131, v114, v115 offset0:2 offset1:3
	v_mad_u32_u24 v8, v1, s40, v2
	s_lshl_b32 s4, s40, 3
	s_nop 0
	v_add_u32_e32 v9, s4, v8
	v_add_u32_e32 v10, s4, v9
	v_add_u32_e32 v11, s4, v10
	s_waitcnt lgkmcnt(0)
	ds_read2_b32 v[12:13], v4 offset1:33
	ds_read2_b32 v[14:15], v4 offset0:66 offset1:99
	ds_read2_b32 v[16:17], v4 offset0:132 offset1:165
	ds_read2_b32 v[18:19], v4 offset0:198 offset1:231
	ds_read2_b32 v[20:21], v4 offset0:8 offset1:41
	ds_read2_b32 v[22:23], v4 offset0:74 offset1:107
	ds_read2_b32 v[24:25], v4 offset0:140 offset1:173
	ds_read2_b32 v[26:27], v4 offset0:206 offset1:239
	ds_read2_b32 v[28:29], v4 offset0:16 offset1:49
	ds_read2_b32 v[30:31], v4 offset0:82 offset1:115
	ds_read2_b32 v[32:33], v4 offset0:148 offset1:181
	ds_read2_b32 v[34:35], v4 offset0:214 offset1:247
	ds_read2_b32 v[36:37], v4 offset0:24 offset1:57
	ds_read2_b32 v[38:39], v4 offset0:90 offset1:123
	ds_read2_b32 v[40:41], v4 offset0:156 offset1:189
	ds_read2_b32 v[42:43], v4 offset0:222 offset1:255
	s_cmp_eq_u32 s41, 0
	s_waitcnt lgkmcnt(0)
	s_cbranch_scc1 .Ltrp3_p5_ng
	v_mul_f32_e32 v12, v116, v12
	v_mul_f32_e32 v13, v117, v13
	v_mul_f32_e32 v14, v118, v14
	v_mul_f32_e32 v15, v119, v15
	v_mul_f32_e32 v16, v120, v16
	v_mul_f32_e32 v17, v121, v17
	v_mul_f32_e32 v18, v122, v18
	v_mul_f32_e32 v19, v123, v19
	v_mul_f32_e32 v20, v116, v20
	v_mul_f32_e32 v21, v117, v21
	v_mul_f32_e32 v22, v118, v22
	v_mul_f32_e32 v23, v119, v23
	v_mul_f32_e32 v24, v120, v24
	v_mul_f32_e32 v25, v121, v25
	v_mul_f32_e32 v26, v122, v26
	v_mul_f32_e32 v27, v123, v27
	v_mul_f32_e32 v28, v116, v28
	v_mul_f32_e32 v29, v117, v29
	v_mul_f32_e32 v30, v118, v30
	v_mul_f32_e32 v31, v119, v31
	v_mul_f32_e32 v32, v120, v32
	v_mul_f32_e32 v33, v121, v33
	v_mul_f32_e32 v34, v122, v34
	v_mul_f32_e32 v35, v123, v35
	v_mul_f32_e32 v36, v116, v36
	v_mul_f32_e32 v37, v117, v37
	v_mul_f32_e32 v38, v118, v38
	v_mul_f32_e32 v39, v119, v39
	v_mul_f32_e32 v40, v120, v40
	v_mul_f32_e32 v41, v121, v41
	v_mul_f32_e32 v42, v122, v42
	v_mul_f32_e32 v43, v123, v43
.Ltrp3_p5_ng:
	v_cvt_pk_bf16_f32 v12, v12, v13
	v_cvt_pk_bf16_f32 v13, v14, v15
	v_cvt_pk_bf16_f32 v14, v16, v17
	v_cvt_pk_bf16_f32 v15, v18, v19
	v_cvt_pk_bf16_f32 v20, v20, v21
	v_cvt_pk_bf16_f32 v21, v22, v23
	v_cvt_pk_bf16_f32 v22, v24, v25
	v_cvt_pk_bf16_f32 v23, v26, v27
	v_cvt_pk_bf16_f32 v28, v28, v29
	v_cvt_pk_bf16_f32 v29, v30, v31
	v_cvt_pk_bf16_f32 v30, v32, v33
	v_cvt_pk_bf16_f32 v31, v34, v35
	v_cvt_pk_bf16_f32 v36, v36, v37
	v_cvt_pk_bf16_f32 v37, v38, v39
	v_cvt_pk_bf16_f32 v38, v40, v41
	v_cvt_pk_bf16_f32 v39, v42, v43
	global_store_dwordx4 v8, v[12:15], s[38:39]
	global_store_dwordx4 v9, v[20:23], s[38:39]
	global_store_dwordx4 v10, v[28:31], s[38:39]
	global_store_dwordx4 v11, v[36:39], s[38:39]
	s_cmp_ge_u32 s20, 0x5600
	s_mov_b32 s43, 0
	s_cbranch_scc1 .Ltrp3_skipB
	s_mov_b32 s26, s20
	s_cmp_lt_u32 s26, 0x2c00
	s_cbranch_scc1 .Ltrp3_i6_s0
	s_sub_u32 s26, s26, 0x2c00
	s_cmp_lt_u32 s26, 0x1600
	s_cbranch_scc1 .Ltrp3_i6_s1
	s_sub_u32 s26, s26, 0x1600
	s_cmp_lt_u32 s26, 0x800
	s_cbranch_scc1 .Ltrp3_i6_s2
	s_sub_u32 s26, s26, 0x800
	s_cmp_lt_u32 s26, 0x400
	s_cbranch_scc1 .Ltrp3_i6_s3
	s_sub_u32 s26, s26, 0x400
	s_cmp_lt_u32 s26, 0x400
	s_cbranch_scc1 .Ltrp3_i6_s4
	s_sub_u32 s26, s26, 0x400
	s_cmp_lt_u32 s26, 0x200
	s_cbranch_scc1 .Ltrp3_i6_s5
	s_sub_u32 s26, s26, 0x200
	s_branch .Ltrp3_i6_s6

.Ltrp3_i6_c:
	s_lshl_b32 s4, s24, 6
	s_mul_i32 s4, s25, s4
	s_lshl_b32 s5, s27, 7
	s_add_u32 s4, s4, s5
	s_add_u32 s10, s22, s4
	s_addc_u32 s11, s23, 0
	v_mad_u32_u24 v6, v1, s24, v2
	s_lshl_b32 s4, s29, 5
	s_mul_i32 s4, s27, s4
	s_lshl_b32 s5, s25, 7
	s_add_u32 s4, s4, s5
	s_add_u32 s4, s4, s28
	s_add_u32 s38, s72, s4
	s_addc_u32 s39, s73, 0
	s_mov_b32 s40, s29
	s_mov_b32 s41, s31
	s_lshl_b32 s4, s25, 8
	s_add_u32 s4, s4, s30
	s_add_u32 s12, s70, s4
	s_addc_u32 s13, s71, 0
	s_lshl_b32 s14, s24, 3
	global_load_dwordx4 v[84:87], v6, s[10:11]
	s_add_u32 s10, s10, s14
	s_addc_u32 s11, s11, 0
	global_load_dwordx4 v[88:91], v6, s[10:11]
	s_add_u32 s10, s10, s14
	s_addc_u32 s11, s11, 0
	global_load_dwordx4 v[92:95], v6, s[10:11]
	s_add_u32 s10, s10, s14
	s_addc_u32 s11, s11, 0
	global_load_dwordx4 v[96:99], v6, s[10:11]
	s_add_u32 s10, s10, s14
	s_addc_u32 s11, s11, 0
	global_load_dwordx4 v[100:103], v6, s[10:11]
	s_add_u32 s10, s10, s14
	s_addc_u32 s11, s11, 0
	global_load_dwordx4 v[104:107], v6, s[10:11]
	s_add_u32 s10, s10, s14
	s_addc_u32 s11, s11, 0
	global_load_dwordx4 v[108:111], v6, s[10:11]
	s_add_u32 s10, s10, s14
	s_addc_u32 s11, s11, 0
	global_load_dwordx4 v[112:115], v6, s[10:11]
	global_load_dwordx4 v[116:119], v5, s[12:13]
	global_load_dwordx4 v[120:123], v5, s[12:13] offset:16
	s_add_u32 s20, s20, s21
	s_mov_b32 s43, 1
.Ltrp3_skipB:
	s_cmp_eq_u32 s42, 0
	s_cbranch_scc1 .LBB0_949
	s_cmp_eq_u32 s43, 0
	s_cbranch_scc1 .Ltrp3_wA0
	s_waitcnt vmcnt(14)
	s_branch .Ltrp3_loopA
.Ltrp3_wA0:
	s_waitcnt vmcnt(0)
	s_branch .Ltrp3_loopA
